# GEMM first-unit prologue: s_waitcnt vmcnt(0) between the K-tile-0 stage loads relaxed to vmcnt(5) (only older ops must be complete); static prio kept
# speedup vs baseline: 1.0170x; 1.0031x over previous
.LBB0_129:
	s_andn2_b64 vcc, exec, s[0:1]
	s_cbranch_vccnz .LBB0_231
	v_bfe_i32 v2, v182, 27, 1
	v_lshlrev_b32_e32 v0, 4, v182
	v_lshrrev_b32_e32 v2, 22, v2
	v_add_u32_e32 v2, v0, v2
	v_and_b32_e32 v2, 0xfffffc00, v2
	v_sub_u32_e32 v2, v0, v2
	s_waitcnt vmcnt(0)
	v_ashrrev_i32_e32 v1, 31, v182
	v_lshrrev_b32_e32 v3, 4, v2
	v_lshrrev_b32_e32 v1, 26, v1
	v_bitop3_b32 v2, v3, v2, 32 bitop3:0x6c
	v_add_u32_e32 v1, v182, v1
	s_waitcnt vmcnt(17)
	v_ashrrev_i32_e32 v4, 31, v2
	v_ashrrev_i32_e32 v1, 6, v1
	v_lshrrev_b32_e32 v4, 26, v4
	v_lshlrev_b32_e32 v3, 3, v1
	v_add_u32_e32 v4, v2, v4
	v_and_b32_e32 v3, -16, v3
	v_ashrrev_i32_e32 v5, 6, v4
	v_lshlrev_b32_e32 v1, 5, v1
	v_add_u32_e32 v3, v5, v3
	v_and_b32_e32 v12, 32, v1
	v_and_b32_e32 v1, 0xc0, v4
	v_sub_u32_e32 v1, v2, v1
	v_lshlrev_b32_e32 v2, 1, v3
	v_lshrrev_b32_e32 v4, 2, v3
	v_and_b32_e32 v5, 3, v5
	s_mov_b32 s1, 0x7fffffe0
	v_ashrrev_i16_sdwa v1, v226, sext(v1) dst_sel:DWORD dst_unused:UNUSED_PAD src0_sel:DWORD src1_sel:BYTE_0
	v_and_b32_e32 v2, 24, v2
	v_and_b32_e32 v4, 4, v4
	v_and_or_b32 v5, v3, s1, v5
	v_bfe_i32 v13, v1, 0, 16
	v_or3_b32 v2, v5, v4, v2
	v_add_u32_e32 v1, v12, v13
	v_mul_lo_u32 v14, s7, v3
	v_mul_lo_u32 v2, s7, v2
	v_add_u32_e32 v0, 0x2000, v0
	v_add_lshl_u32 v184, v14, v1, 1
	v_add_lshl_u32 v186, v2, v1, 1
	v_ashrrev_i32_e32 v1, 31, v0
	v_lshrrev_b32_e32 v1, 22, v1
	v_add_u32_e32 v1, v0, v1
	v_ashrrev_i32_e32 v1, 10, v1
	v_mul_i32_i24_e32 v2, 0x400, v1
	v_sub_u32_e32 v0, v0, v2
	v_lshrrev_b32_e32 v2, 4, v0
	v_bitop3_b32 v0, v2, v0, 32 bitop3:0x6c
	v_ashrrev_i32_e32 v3, 31, v0
	s_lshl_b32 s98, s7, 8
	s_mov_b32 s99, s81
	v_lshrrev_b32_e32 v3, 26, v3
	s_lshl_b64 s[36:37], s[98:99], 1
	s_ashr_i32 s4, s19, 31
	v_lshlrev_b32_e32 v2, 3, v1
	v_add_u32_e32 v3, v0, v3
	s_mul_i32 s4, s36, s4
	s_mul_hi_u32 s5, s36, s19
	s_ashr_i32 s8, s18, 31
	v_and_b32_e32 v2, -16, v2
	v_ashrrev_i32_e32 v4, 6, v3
	s_add_i32 s4, s5, s4
	s_bfe_u32 s5, s7, 0x10017
	s_mul_i32 s8, s36, s8
	s_mul_hi_u32 s9, s36, s18
	s_ashr_i32 s0, s12, 6
	v_add_u32_e32 v2, v4, v2
	v_lshlrev_b32_e32 v1, 5, v1
	v_and_b32_e32 v4, 3, v4
	s_mul_i32 s6, s5, s19
	s_add_i32 s8, s9, s8
	s_mul_i32 s5, s5, s18
	v_and_b32_e32 v15, 32, v1
	v_and_b32_e32 v1, 0xc0, v3
	v_and_or_b32 v4, v2, s1, v4
	s_ashr_i32 s1, s12, 8
	s_lshl_b32 s33, s0, 10
	s_add_i32 s4, s4, s6
	s_add_i32 s8, s8, s5
	s_mul_i32 s5, s36, s18
	v_sub_u32_e32 v0, v0, v1
	v_lshlrev_b32_e32 v1, 1, v2
	v_lshrrev_b32_e32 v3, 2, v2
	s_add_u32 s68, s88, s5
	v_ashrrev_i16_sdwa v0, v226, sext(v0) dst_sel:DWORD dst_unused:UNUSED_PAD src0_sel:DWORD src1_sel:BYTE_0
	v_and_b32_e32 v1, 24, v1
	v_and_b32_e32 v3, 4, v3
	s_addc_u32 s69, s89, s8
	s_add_i32 s76, s33, 0
	v_bfe_i32 v16, v0, 0, 16
	v_or3_b32 v1, v4, v3, v1
	s_add_i32 m0, s76, 0x10000
	v_add_u32_e32 v0, v15, v16
	v_mul_lo_u32 v1, s7, v1
	s_mul_i32 s6, s36, s19
	global_load_lds_dwordx4 v186, s[68:69]
	s_add_i32 m0, s76, 0x12000
	v_add_lshl_u32 v190, v1, v0, 1
	s_add_u32 s70, s84, s6
	v_mul_lo_u32 v17, s7, v2
	global_load_lds_dwordx4 v190, s[68:69]
	s_addc_u32 s71, s85, s4
	s_mov_b32 m0, s76
	s_add_i32 s4, s76, 0x2000
	v_add_lshl_u32 v188, v17, v0, 1
	global_load_lds_dwordx4 v184, s[70:71]
	s_mov_b32 m0, s4
	s_add_u32 s8, s68, s98
	global_load_lds_dwordx4 v188, s[70:71]
	s_addc_u32 s9, s69, 0
	s_add_i32 m0, s76, 0x14000
	v_mov_b32_e32 v187, v180
	v_mov_b32_e32 v191, v180
	global_load_lds_dwordx4 v186, s[8:9]
	s_add_i32 m0, s76, 0x16000
	s_waitcnt vmcnt(5)
	v_lshl_add_u64 v[8:9], s[8:9], 0, v[186:187]
	v_lshl_add_u64 v[10:11], s[8:9], 0, v[190:191]
	global_load_lds_dwordx4 v190, s[8:9]
	s_add_u32 s8, s70, s98
	s_addc_u32 s9, s71, 0
	s_add_i32 s5, s76, 0x4000
	s_mov_b32 m0, s5
	s_add_i32 s6, s76, 0x6000
	global_load_lds_dwordx4 v184, s[8:9]
	s_mov_b32 m0, s6
	s_load_dword s74, s[24:25], 0x0
	global_load_lds_dwordx4 v188, s[8:9]
	v_mov_b32_e32 v185, v180
	v_mov_b32_e32 v189, v180
	v_lshl_add_u64 v[0:1], s[68:69], 0, v[186:187]
	v_lshl_add_u64 v[2:3], s[68:69], 0, v[190:191]
	v_lshl_add_u64 v[4:5], s[70:71], 0, v[184:185]
	v_lshl_add_u64 v[6:7], s[70:71], 0, v[188:189]
	s_cmp_lg_u32 s1, 1
	v_writelane_b32 v240, s12, 12
	s_cbranch_scc1 .LBB0_132
	s_setprio 1
	s_barrier
